# v22: v21 + rwkv_prep S2 epilogues rewritten (fma-form sigmoid, merged constants, 4-wide interleave without hazard nops, paired bf16 LDS writes)
# speedup vs baseline: 1.0108x; 1.0002x over previous
.LBB0_519:
	v_readlane_b32 s12, v255, 29
	v_readlane_b32 s20, v255, 37
	v_readlane_b32 s21, v255, 38
	v_readlane_b32 s13, v255, 30
	v_readlane_b32 s14, v255, 31
	v_readlane_b32 s15, v255, 32
	v_readlane_b32 s16, v255, 33
	v_readlane_b32 s17, v255, 34
	v_readlane_b32 s18, v255, 35
	v_readlane_b32 s19, v255, 36
	v_readlane_b32 s22, v255, 39
	v_readlane_b32 s23, v255, 40
	v_readlane_b32 s24, v255, 41
	v_readlane_b32 s25, v255, 42
	v_readlane_b32 s26, v255, 43
	v_readlane_b32 s27, v255, 44
	v_lshl_add_u32 v24, v18, 1, v21
	s_waitcnt vmcnt(0)
	v_mul_f32_e32 v87, 0xbfb8aa3b, v86
	v_fmamk_f32 v88, v0, 0xbfb8aa3b, v87
	v_fmamk_f32 v89, v1, 0xbfb8aa3b, v87
	v_fmamk_f32 v90, v2, 0xbfb8aa3b, v87
	v_fmamk_f32 v91, v3, 0xbfb8aa3b, v87
	v_exp_f32_e32 v88, v88
	v_exp_f32_e32 v89, v89
	v_exp_f32_e32 v90, v90
	v_exp_f32_e32 v91, v91
	v_add_f32_e32 v88, 1.0, v88
	v_add_f32_e32 v89, 1.0, v89
	v_add_f32_e32 v90, 1.0, v90
	v_add_f32_e32 v91, 1.0, v91
	v_rcp_f32_e32 v88, v88
	v_rcp_f32_e32 v89, v89
	v_rcp_f32_e32 v90, v90
	v_rcp_f32_e32 v91, v91
	v_cvt_pk_bf16_f32 v88, v88, v89
	v_cvt_pk_bf16_f32 v90, v90, v91
	ds_write_b16 v24, v88 offset:9216
	ds_write_b16_d16_hi v24, v88 offset:10256
	ds_write_b16 v24, v90 offset:11296
	ds_write_b16_d16_hi v24, v90 offset:12336
	v_fmamk_f32 v88, v4, 0xbfb8aa3b, v87
	v_fmamk_f32 v89, v5, 0xbfb8aa3b, v87
	v_fmamk_f32 v90, v6, 0xbfb8aa3b, v87
	v_fmamk_f32 v91, v7, 0xbfb8aa3b, v87
	v_exp_f32_e32 v88, v88
	v_exp_f32_e32 v89, v89
	v_exp_f32_e32 v90, v90
	v_exp_f32_e32 v91, v91
	v_add_f32_e32 v88, 1.0, v88
	v_add_f32_e32 v89, 1.0, v89
	v_add_f32_e32 v90, 1.0, v90
	v_add_f32_e32 v91, 1.0, v91
	v_rcp_f32_e32 v88, v88
	v_rcp_f32_e32 v89, v89
	v_rcp_f32_e32 v90, v90
	v_rcp_f32_e32 v91, v91
	v_cvt_pk_bf16_f32 v88, v88, v89
	v_cvt_pk_bf16_f32 v90, v90, v91
	ds_write_b16 v24, v88 offset:17536
	ds_write_b16_d16_hi v24, v88 offset:18576
	ds_write_b16 v24, v90 offset:19616
	ds_write_b16_d16_hi v24, v90 offset:20656
	v_fmamk_f32 v88, v8, 0xbfb8aa3b, v87
	v_fmamk_f32 v89, v9, 0xbfb8aa3b, v87
	v_fmamk_f32 v90, v10, 0xbfb8aa3b, v87
	v_fmamk_f32 v91, v11, 0xbfb8aa3b, v87
	v_exp_f32_e32 v88, v88
	v_exp_f32_e32 v89, v89
	v_exp_f32_e32 v90, v90
	v_exp_f32_e32 v91, v91
	v_add_f32_e32 v88, 1.0, v88
	v_add_f32_e32 v89, 1.0, v89
	v_add_f32_e32 v90, 1.0, v90
	v_add_f32_e32 v91, 1.0, v91
	v_rcp_f32_e32 v88, v88
	v_rcp_f32_e32 v89, v89
	v_rcp_f32_e32 v90, v90
	v_rcp_f32_e32 v91, v91
	v_cvt_pk_bf16_f32 v88, v88, v89
	v_cvt_pk_bf16_f32 v90, v90, v91
	ds_write_b16 v24, v88 offset:25856
	ds_write_b16_d16_hi v24, v88 offset:26896
	ds_write_b16 v24, v90 offset:27936
	ds_write_b16_d16_hi v24, v90 offset:28976
	v_fmamk_f32 v88, v12, 0xbfb8aa3b, v87
	v_fmamk_f32 v89, v13, 0xbfb8aa3b, v87
	v_fmamk_f32 v90, v14, 0xbfb8aa3b, v87
	v_fmamk_f32 v91, v15, 0xbfb8aa3b, v87
	v_exp_f32_e32 v88, v88
	v_exp_f32_e32 v89, v89
	v_exp_f32_e32 v90, v90
	v_exp_f32_e32 v91, v91
	v_add_f32_e32 v88, 1.0, v88
	v_add_f32_e32 v89, 1.0, v89
	v_add_f32_e32 v90, 1.0, v90
	v_add_f32_e32 v91, 1.0, v91
	v_rcp_f32_e32 v88, v88
	v_rcp_f32_e32 v89, v89
	v_rcp_f32_e32 v90, v90
	v_rcp_f32_e32 v91, v91
	v_cvt_pk_bf16_f32 v88, v88, v89
	v_cvt_pk_bf16_f32 v90, v90, v91
	ds_write_b16 v24, v88 offset:34176
	ds_write_b16_d16_hi v24, v88 offset:35216
	ds_write_b16 v24, v90 offset:36256
	ds_write_b16_d16_hi v24, v90 offset:37296
	s_branch .LBB0_516
.LBB0_520:
	v_readlane_b32 s12, v255, 29
	v_lshlrev_b64 v[18:19], 2, v[18:19]
	v_readlane_b32 s16, v255, 33
	v_readlane_b32 s17, v255, 34
	v_readlane_b32 s13, v255, 30
	v_readlane_b32 s14, v255, 31
	v_lshl_add_u64 v[18:19], v[16:17], 0, v[18:19]
	v_readlane_b32 s15, v255, 32
	v_readlane_b32 s18, v255, 35
	v_readlane_b32 s19, v255, 36
	v_readlane_b32 s20, v255, 37
	v_readlane_b32 s21, v255, 38
	v_readlane_b32 s22, v255, 39
	v_readlane_b32 s23, v255, 40
	v_readlane_b32 s24, v255, 41
	v_readlane_b32 s25, v255, 42
	v_readlane_b32 s26, v255, 43
	v_readlane_b32 s27, v255, 44
	s_mov_b32 s5, 0
	s_mov_b32 s4, 0x1000
	v_lshl_add_u64 v[128:129], v[18:19], 0, s[4:5]
	s_mov_b32 s4, 0x5000
	v_lshl_add_u64 v[130:131], v[18:19], 0, s[4:5]
	s_mov_b32 s4, 0x9000
	v_lshl_add_u64 v[132:133], v[18:19], 0, s[4:5]
	s_mov_b32 s4, 0xd000
	v_lshl_add_u64 v[134:135], v[18:19], 0, s[4:5]
	s_waitcnt vmcnt(0)
	v_mul_f32_e32 v87, 0xbfb8aa3b, v86
	v_fmamk_f32 v88, v0, 0xbfb8aa3b, v87
	v_fmamk_f32 v89, v1, 0xbfb8aa3b, v87
	v_fmamk_f32 v90, v2, 0xbfb8aa3b, v87
	v_fmamk_f32 v91, v3, 0xbfb8aa3b, v87
	v_exp_f32_e32 v88, v88
	v_exp_f32_e32 v89, v89
	v_exp_f32_e32 v90, v90
	v_exp_f32_e32 v91, v91
	v_add_f32_e32 v88, 1.0, v88
	v_add_f32_e32 v89, 1.0, v89
	v_add_f32_e32 v90, 1.0, v90
	v_add_f32_e32 v91, 1.0, v91
	v_rcp_f32_e32 v88, v88
	v_rcp_f32_e32 v89, v89
	v_rcp_f32_e32 v90, v90
	v_rcp_f32_e32 v91, v91
	v_mul_f32_e32 v88, 0xbf60028a, v88
	v_mul_f32_e32 v89, 0xbf60028a, v89
	v_mul_f32_e32 v90, 0xbf60028a, v90
	v_mul_f32_e32 v91, 0xbf60028a, v91
	v_exp_f32_e32 v88, v88
	v_exp_f32_e32 v89, v89
	v_exp_f32_e32 v90, v90
	v_exp_f32_e32 v91, v91
	global_store_dword v[128:129], v88, off offset:-4096 nt
	global_store_dword v[128:129], v89, off offset:-2048 nt
	global_store_dword v[128:129], v90, off nt
	global_store_dword v[128:129], v91, off offset:2048 nt
	v_fmamk_f32 v88, v4, 0xbfb8aa3b, v87
	v_fmamk_f32 v89, v5, 0xbfb8aa3b, v87
	v_fmamk_f32 v90, v6, 0xbfb8aa3b, v87
	v_fmamk_f32 v91, v7, 0xbfb8aa3b, v87
	v_exp_f32_e32 v88, v88
	v_exp_f32_e32 v89, v89
	v_exp_f32_e32 v90, v90
	v_exp_f32_e32 v91, v91
	v_add_f32_e32 v88, 1.0, v88
	v_add_f32_e32 v89, 1.0, v89
	v_add_f32_e32 v90, 1.0, v90
	v_add_f32_e32 v91, 1.0, v91
	v_rcp_f32_e32 v88, v88
	v_rcp_f32_e32 v89, v89
	v_rcp_f32_e32 v90, v90
	v_rcp_f32_e32 v91, v91
	v_mul_f32_e32 v88, 0xbf60028a, v88
	v_mul_f32_e32 v89, 0xbf60028a, v89
	v_mul_f32_e32 v90, 0xbf60028a, v90
	v_mul_f32_e32 v91, 0xbf60028a, v91
	v_exp_f32_e32 v88, v88
	v_exp_f32_e32 v89, v89
	v_exp_f32_e32 v90, v90
	v_exp_f32_e32 v91, v91
	global_store_dword v[130:131], v88, off offset:-4096 nt
	global_store_dword v[130:131], v89, off offset:-2048 nt
	global_store_dword v[130:131], v90, off nt
	global_store_dword v[130:131], v91, off offset:2048 nt
	v_fmamk_f32 v88, v8, 0xbfb8aa3b, v87
	v_fmamk_f32 v89, v9, 0xbfb8aa3b, v87
	v_fmamk_f32 v90, v10, 0xbfb8aa3b, v87
	v_fmamk_f32 v91, v11, 0xbfb8aa3b, v87
	v_exp_f32_e32 v88, v88
	v_exp_f32_e32 v89, v89
	v_exp_f32_e32 v90, v90
	v_exp_f32_e32 v91, v91
	v_add_f32_e32 v88, 1.0, v88
	v_add_f32_e32 v89, 1.0, v89
	v_add_f32_e32 v90, 1.0, v90
	v_add_f32_e32 v91, 1.0, v91
	v_rcp_f32_e32 v88, v88
	v_rcp_f32_e32 v89, v89
	v_rcp_f32_e32 v90, v90
	v_rcp_f32_e32 v91, v91
	v_mul_f32_e32 v88, 0xbf60028a, v88
	v_mul_f32_e32 v89, 0xbf60028a, v89
	v_mul_f32_e32 v90, 0xbf60028a, v90
	v_mul_f32_e32 v91, 0xbf60028a, v91
	v_exp_f32_e32 v88, v88
	v_exp_f32_e32 v89, v89
	v_exp_f32_e32 v90, v90
	v_exp_f32_e32 v91, v91
	global_store_dword v[132:133], v88, off offset:-4096 nt
	global_store_dword v[132:133], v89, off offset:-2048 nt
	global_store_dword v[132:133], v90, off nt
	global_store_dword v[132:133], v91, off offset:2048 nt
	v_fmamk_f32 v88, v12, 0xbfb8aa3b, v87
	v_fmamk_f32 v89, v13, 0xbfb8aa3b, v87
	v_fmamk_f32 v90, v14, 0xbfb8aa3b, v87
	v_fmamk_f32 v91, v15, 0xbfb8aa3b, v87
	v_exp_f32_e32 v88, v88
	v_exp_f32_e32 v89, v89
	v_exp_f32_e32 v90, v90
	v_exp_f32_e32 v91, v91
	v_add_f32_e32 v88, 1.0, v88
	v_add_f32_e32 v89, 1.0, v89
	v_add_f32_e32 v90, 1.0, v90
	v_add_f32_e32 v91, 1.0, v91
	v_rcp_f32_e32 v88, v88
	v_rcp_f32_e32 v89, v89
	v_rcp_f32_e32 v90, v90
	v_rcp_f32_e32 v91, v91
	v_mul_f32_e32 v88, 0xbf60028a, v88
	v_mul_f32_e32 v89, 0xbf60028a, v89
	v_mul_f32_e32 v90, 0xbf60028a, v90
	v_mul_f32_e32 v91, 0xbf60028a, v91
	v_exp_f32_e32 v88, v88
	v_exp_f32_e32 v89, v89
	v_exp_f32_e32 v90, v90
	v_exp_f32_e32 v91, v91
	global_store_dword v[134:135], v88, off offset:-4096 nt
	global_store_dword v[134:135], v89, off offset:-2048 nt
	global_store_dword v[134:135], v90, off nt
	global_store_dword v[134:135], v91, off offset:2048 nt
	s_branch .LBB0_516
